# v67: ssd_out first z tile address recomputed early so its load travels with the first S3 prefetch loads
# baseline (speedup 1.0000x reference)
.LBB0_1328:
	s_or_b64 exec, exec, s[0:1]
	v_add_co_u32_e32 v62, vcc, 0x12000, v62
	s_waitcnt vmcnt(4)
	v_lshlrev_b32_e32 v66, 16, v38
	v_addc_co_u32_e32 v63, vcc, 0, v63, vcc
	global_load_dwordx4 v[62:65], v[62:63], off
	s_lshr_b32 s98, s74, 2
	s_and_b32 s98, s98, 31
	s_lshl_b32 s98, s98, 7
	v_cndmask_b32_e64 v234, 0, 1, s[30:31]
	v_lshlrev_b32_e32 v234, 6, v234
	v_or_b32_e32 v234, s98, v234
	v_add_u32_e32 v234, s33, v234
	v_add_u32_e32 v234, v234, v176
	s_movk_i32 s99, 0x2e00
	v_mad_i64_i32 v[234:235], s[100:101], v234, s99, v[110:111]
	s_lshr_b32 s98, s74, 1
	s_and_b32 s98, s98, 1
	s_lshl_b32 s98, s98, 10
	s_mov_b32 s99, 0
	v_lshl_add_u64 v[234:235], v[234:235], 0, s[98:99]
	v_readlane_b32 s98, v255, 13
	v_readlane_b32 s99, v255, 14
	s_mov_b64 s[100:101], 0x8c01800
	s_nop 0
	v_lshl_add_u64 v[234:235], s[98:99], 0, v[234:235]
	v_lshl_add_u64 v[236:237], v[234:235], 0, s[100:101]
	global_load_dwordx4 v[226:229], v[236:237], off
	s_mov_b64 s[100:101], 0x8c18800
	v_lshl_add_u64 v[236:237], v[234:235], 0, s[100:101]
	global_load_dwordx4 v[230:233], v[236:237], off
	v_and_b32_e32 v67, 0xffff0000, v38
	v_lshlrev_b32_e32 v68, 16, v39
	v_and_b32_e32 v69, 0xffff0000, v39
	s_waitcnt vmcnt(6)
	v_pk_mul_f32 v[66:67], v[122:123], v[66:67] op_sel_hi:[0,1]
	v_pk_mul_f32 v[68:69], v[122:123], v[68:69] op_sel_hi:[0,1]
	v_cvt_pk_bf16_f32 v66, v66, v67
	v_cvt_pk_bf16_f32 v67, v68, v69
	v_lshlrev_b32_e32 v68, 16, v40
	v_and_b32_e32 v69, 0xffff0000, v40
	v_lshlrev_b32_e32 v70, 16, v41
	v_and_b32_e32 v71, 0xffff0000, v41
	v_pk_mul_f32 v[68:69], v[122:123], v[68:69] op_sel_hi:[0,1]
	v_pk_mul_f32 v[70:71], v[122:123], v[70:71] op_sel_hi:[0,1]
	v_cvt_pk_bf16_f32 v68, v68, v69
	v_cvt_pk_bf16_f32 v69, v70, v71
	ds_write_b128 v127, v[66:69] offset:17408
	s_waitcnt vmcnt(5)
	ds_write_b128 v127, v[42:45] offset:52224
	s_and_saveexec_b64 s[0:1], s[10:11]
	s_cbranch_execz .LBB0_1330
	v_lshlrev_b32_e32 v66, 16, v34
	v_and_b32_e32 v67, 0xffff0000, v34
	v_lshlrev_b32_e32 v68, 16, v35
	v_and_b32_e32 v69, 0xffff0000, v35
	v_pk_mul_f32 v[66:67], v[124:125], v[66:67] op_sel_hi:[0,1]
	v_pk_mul_f32 v[68:69], v[124:125], v[68:69] op_sel_hi:[0,1]
	v_cvt_pk_bf16_f32 v66, v66, v67
	v_cvt_pk_bf16_f32 v67, v68, v69
	v_lshlrev_b32_e32 v68, 16, v36
	v_and_b32_e32 v69, 0xffff0000, v36
	v_lshlrev_b32_e32 v70, 16, v37
	v_and_b32_e32 v71, 0xffff0000, v37
	v_pk_mul_f32 v[68:69], v[124:125], v[68:69] op_sel_hi:[0,1]
	v_pk_mul_f32 v[70:71], v[124:125], v[70:71] op_sel_hi:[0,1]
	v_cvt_pk_bf16_f32 v68, v68, v69
	v_cvt_pk_bf16_f32 v69, v70, v71
	ds_write_b128 v127, v[66:69] offset:26112
.LBB0_1330:
	s_or_b64 exec, exec, s[0:1]
	s_waitcnt vmcnt(4)
	ds_write_b128 v127, v[54:57] offset:60928
	s_and_saveexec_b64 s[0:1], s[12:13]
	s_cbranch_execz .LBB0_1332
	v_lshlrev_b32_e32 v66, 16, v46
	v_and_b32_e32 v67, 0xffff0000, v46
	v_lshlrev_b32_e32 v68, 16, v47
	v_and_b32_e32 v69, 0xffff0000, v47
	v_pk_mul_f32 v[66:67], v[126:127], v[66:67] op_sel_hi:[0,1]
	v_pk_mul_f32 v[68:69], v[126:127], v[68:69] op_sel_hi:[0,1]
	v_cvt_pk_bf16_f32 v66, v66, v67
	v_cvt_pk_bf16_f32 v67, v68, v69
	v_lshlrev_b32_e32 v68, 16, v48
	v_and_b32_e32 v69, 0xffff0000, v48
	v_lshlrev_b32_e32 v70, 16, v49
	v_and_b32_e32 v71, 0xffff0000, v49
	v_pk_mul_f32 v[68:69], v[126:127], v[68:69] op_sel_hi:[0,1]
	v_pk_mul_f32 v[70:71], v[126:127], v[70:71] op_sel_hi:[0,1]
	v_cvt_pk_bf16_f32 v68, v68, v69
	v_cvt_pk_bf16_f32 v69, v70, v71
	ds_write_b128 v127, v[66:69] offset:34816
.LBB0_1332:
	s_or_b64 exec, exec, s[0:1]
	s_lshl_b32 s0, s24, 9
	v_writelane_b32 v255, s0, 48
	s_waitcnt vmcnt(3)
	ds_write_b128 v158, v[58:61] offset:17408
	s_and_saveexec_b64 s[0:1], s[14:15]
	s_cbranch_execz .LBB0_1334
	v_lshlrev_b32_e32 v66, 16, v50
	v_and_b32_e32 v67, 0xffff0000, v50
	v_lshlrev_b32_e32 v68, 16, v51
	v_and_b32_e32 v69, 0xffff0000, v51
	v_pk_mul_f32 v[66:67], v[128:129], v[66:67] op_sel_hi:[0,1]
	v_pk_mul_f32 v[68:69], v[128:129], v[68:69] op_sel_hi:[0,1]
	v_cvt_pk_bf16_f32 v66, v66, v67
	v_cvt_pk_bf16_f32 v67, v68, v69
	v_lshlrev_b32_e32 v68, 16, v52
	v_and_b32_e32 v69, 0xffff0000, v52
	v_lshlrev_b32_e32 v70, 16, v53
	v_and_b32_e32 v71, 0xffff0000, v53
	v_pk_mul_f32 v[68:69], v[128:129], v[68:69] op_sel_hi:[0,1]
	v_pk_mul_f32 v[70:71], v[128:129], v[70:71] op_sel_hi:[0,1]
	v_cvt_pk_bf16_f32 v68, v68, v69
	v_cvt_pk_bf16_f32 v69, v70, v71
	ds_write_b128 v127, v[66:69] offset:43520
.LBB0_1334:
	s_or_b64 exec, exec, s[0:1]
	v_or_b32_e32 v70, s34, v157
	s_lshr_b32 s1, s74, 1
	v_or_b32_e32 v66, s72, v70
	s_lshr_b32 s0, s74, 2
	v_writelane_b32 v255, s34, 49
	v_ashrrev_i32_e32 v67, 31, v66
	s_and_b32 s42, s1, 1
	v_lshlrev_b64 v[66:67], 6, v[66:67]
	s_and_b32 s0, s0, 31
	s_lshl_b32 s43, s42, 3
	v_readlane_b32 s1, v255, 31
	v_readlane_b32 s56, v254, 46
	v_lshl_add_u64 v[66:67], s[28:29], 0, v[66:67]
	s_lshl_b32 s52, s18, 2
	s_lshl_b32 s40, s0, 7
	s_lshl_b32 s41, s0, 4
	s_add_i32 s0, s1, s43
	v_readlane_b32 s64, v254, 54
	v_readlane_b32 s65, v254, 55
	v_lshl_add_u64 v[66:67], v[66:67], 0, s[52:53]
	s_lshl_b32 s52, s42, 10
	s_lshl_b32 s0, s0, 2
	s_mov_b64 s[20:21], s[64:65]
	s_add_u32 s54, s20, s0
	v_or_b32_e32 v72, 1, v70
	v_cmp_gt_u32_e32 vcc, v160, v70
	s_addc_u32 s55, s21, 0
	v_or_b32_e32 v73, 2, v70
	s_or_b64 s[82:83], s[2:3], vcc
	v_cmp_gt_u32_e32 vcc, v160, v72
	v_or_b32_e32 v74, 3, v70
	s_or_b64 s[86:87], s[2:3], vcc
	v_cmp_gt_u32_e32 vcc, v160, v73
	s_or_b64 s[88:89], s[2:3], vcc
	v_cmp_gt_u32_e32 vcc, v160, v74
	s_or_b64 s[90:91], s[2:3], vcc
	v_cmp_gt_u32_e64 s[2:3], v161, v70
	v_readlane_b32 s57, v254, 47
	v_readlane_b32 s58, v254, 48
	v_readlane_b32 s59, v254, 49
	v_readlane_b32 s60, v254, 50
	v_readlane_b32 s61, v254, 51
	v_readlane_b32 s62, v254, 52
	v_readlane_b32 s63, v254, 53
	v_readlane_b32 s66, v254, 56
	v_readlane_b32 s67, v254, 57
	v_readlane_b32 s68, v254, 58
	v_readlane_b32 s69, v254, 59
	v_readlane_b32 s70, v254, 60
	v_readlane_b32 s71, v254, 61
	v_writelane_b32 v254, s2, 25
	v_writelane_b32 v255, s30, 50
	s_lshl_b32 s0, s1, 2
	v_writelane_b32 v254, s3, 26
	v_cmp_gt_u32_e64 s[2:3], v161, v72
	v_writelane_b32 v255, s31, 51
	s_cmp_gt_u32 s38, 1
	v_writelane_b32 v254, s2, 7
	v_cmp_gt_u32_e32 vcc, v162, v70
	s_cselect_b64 s[94:95], -1, 0
	v_writelane_b32 v254, s3, 8
	v_cmp_gt_u32_e64 s[2:3], v161, v73
	s_mov_b32 s1, s53
	v_lshl_add_u64 v[130:131], v[66:67], 0, s[0:1]
	v_writelane_b32 v255, s2, 19
	v_cndmask_b32_e64 v68, 0, 1, s[30:31]
	v_lshlrev_b32_e32 v69, 6, v68
	v_writelane_b32 v255, s3, 20
	v_cmp_gt_u32_e64 s[2:3], v161, v74
	v_lshl_add_u32 v115, v68, 11, v177
	v_or_b32_e32 v68, s40, v69
	v_writelane_b32 v255, s2, 21
	v_mul_u32_u24_e32 v71, 0x110, v70
	v_mov_b32_e32 v134, 0
	v_writelane_b32 v255, s3, 22
	s_or_b64 s[2:3], s[4:5], vcc
	v_writelane_b32 v255, s2, 17
	v_cmp_gt_u32_e32 vcc, v162, v72
	v_cmp_gt_u32_e64 s[0:1], v1, v70
	v_writelane_b32 v255, s3, 18
	s_or_b64 s[2:3], s[4:5], vcc
	v_writelane_b32 v255, s2, 23
	v_cmp_gt_u32_e32 vcc, v162, v73
	v_cmp_gt_u32_e64 s[18:19], v1, v72
	v_writelane_b32 v255, s3, 24
	s_or_b64 s[2:3], s[4:5], vcc
	v_writelane_b32 v255, s2, 52
	v_cmp_gt_u32_e32 vcc, v162, v74
	v_cmp_gt_u32_e64 s[20:21], v1, v73
	v_writelane_b32 v255, s3, 53
	s_or_b64 s[2:3], s[4:5], vcc
	v_cmp_gt_u32_e32 vcc, v164, v70
	v_writelane_b32 v255, s2, 54
	s_or_b64 s[80:81], s[16:17], vcc
	v_cmp_gt_u32_e32 vcc, v164, v72
	v_writelane_b32 v255, s3, 55
	s_or_b64 s[2:3], s[16:17], vcc
	v_cmp_gt_u32_e32 vcc, v164, v73
	s_or_b64 s[68:69], s[16:17], vcc
	v_cmp_gt_u32_e32 vcc, v164, v74
	s_or_b64 s[62:63], s[16:17], vcc
	s_cmp_gt_u32 s38, 5
	v_cmp_gt_u32_e32 vcc, v166, v70
	s_cselect_b64 s[56:57], -1, 0
	s_or_b64 s[16:17], s[36:37], vcc
	v_cmp_gt_u32_e32 vcc, v166, v72
	s_or_b64 s[4:5], s[36:37], vcc
	v_cmp_gt_u32_e32 vcc, v166, v73
	s_or_b64 s[60:61], s[36:37], vcc
	v_cmp_gt_u32_e32 vcc, v166, v74
	s_or_b64 s[58:59], s[36:37], vcc
	s_and_b32 s36, s38, 6
	s_cmp_eq_u32 s36, 6
	s_cselect_b64 s[84:85], -1, 0
	s_add_i32 s36, s40, s33
	v_add_u32_e32 v66, s36, v105
	v_ashrrev_i32_e32 v67, 31, v66
	v_lshlrev_b64 v[136:137], 6, v[66:67]
	s_add_i32 s38, s39, s41
	v_or_b32_e32 v67, v104, v136
	s_add_i32 s38, s38, s43
	v_lshl_or_b32 v136, s42, 5, v67
	v_mad_i64_i32 v[66:67], s[42:43], v66, s44, 0
	v_or_b32_e32 v66, v108, v66
	v_lshl_add_u64 v[138:139], v[66:67], 0, s[52:53]
	v_add_u32_e32 v66, s33, v68
	v_add_u32_e32 v66, v66, v176
	v_ashrrev_i32_e32 v67, 31, v66
	s_ashr_i32 s39, s38, 31
	v_lshlrev_b64 v[68:69], 12, v[66:67]
	s_movk_i32 s33, 0x2e00
	s_lshl_b64 s[38:39], s[38:39], 14
	v_lshl_add_u64 v[68:69], v[110:111], 0, v[68:69]
	v_mad_i64_i32 v[66:67], s[42:43], v66, s33, v[110:111]
	v_cmp_gt_u32_e64 s[22:23], v1, v74
	v_cmp_gt_u32_e64 s[34:35], v163, v70
	v_cmp_gt_u32_e64 s[30:31], v163, v72
	v_mov_b32_e32 v133, s39
	v_or_b32_e32 v132, s38, v106
	v_cmp_gt_u32_e64 s[92:93], v163, v73
	v_cmp_gt_u32_e64 s[96:97], v163, v74
	v_lshl_add_u64 v[142:143], v[68:69], 0, s[52:53]
	v_lshl_add_u64 v[144:145], v[66:67], 0, s[52:53]
	global_load_dword v240, v[130:131], off
	global_load_dword v241, v[130:131], off offset:64
	global_load_dword v242, v[130:131], off offset:128
	global_load_dword v243, v[130:131], off offset:192
	s_mov_b32 s33, 0
	v_add_u32_e32 v117, v159, v71
	v_mov_b32_e32 v135, v134
	v_mov_b32_e32 v140, v134
	v_mov_b32_e32 v141, v134
	v_cmp_gt_u32_e64 s[78:79], v165, v70
	v_cmp_gt_u32_e64 s[24:25], v165, v72
	v_cmp_gt_u32_e64 s[26:27], v165, v73
	v_cmp_gt_u32_e64 s[28:29], v165, v74
	s_mov_b64 s[64:65], 0
	s_waitcnt vmcnt(0)
	ds_write_b128 v158, v[62:65] offset:26112
	ds_write_b128 v180, v[226:229]
	ds_write_b128 v180, v[230:233] offset:1024
	s_branch .LBB0_1337
